# on top of v32: non-temporal (nt) hint on the 64 G1 epilogue tile stores per layer (P1/PM/PS/VT outputs are only re-read after a grid barrier)
# speedup vs baseline: 1.0148x; 1.0142x over previous
.LBB0_188:
	v_lshlrev_b32_e32 v136, 1, v136
	v_cvt_pk_bf16_f32 v178, v124, v125
	v_cvt_pk_bf16_f32 v179, v126, v127
	v_cvt_pk_bf16_f32 v180, v120, v121
	v_cvt_pk_bf16_f32 v181, v122, v123
	v_lshl_add_u64 v[154:155], v[154:155], 0, v[136:137]
	global_store_dwordx4 v[154:155], v[178:181], off nt
	v_or_b32_e32 v177, s39, v140
	v_cndmask_b32_e64 v136, 0, 1, s[48:49]
	v_ashrrev_i32_e32 v154, 6, v177
	s_mov_b64 s[50:51], -1
	v_cmp_ne_u32_e64 s[8:9], 1, v136
	s_andn2_b64 vcc, exec, s[48:49]
	v_ashrrev_i32_e32 v155, 31, v154
	s_cbranch_vccnz .LBB0_190
	v_lshlrev_b64 v[160:161], 17, v[154:155]
	v_lshl_add_u64 v[160:161], s[22:23], 0, v[160:161]
	v_lshl_add_u64 v[160:161], v[160:161], 0, v[156:157]
	s_mov_b64 s[50:51], 0

.LBB0_192:
	v_lshlrev_b32_e32 v136, 1, v136
	v_cvt_pk_bf16_f32 v156, v116, v117
	v_cvt_pk_bf16_f32 v157, v118, v119
	v_cvt_pk_bf16_f32 v158, v112, v113
	v_cvt_pk_bf16_f32 v159, v114, v115
	v_lshl_add_u64 v[160:161], v[160:161], 0, v[136:137]
	global_store_dwordx4 v[160:161], v[156:159], off nt
	s_nop 1
	v_add_u32_e32 v156, s12, v163
	v_ashrrev_i32_e32 v157, 31, v156
	v_lshlrev_b64 v[158:159], 7, v[156:157]
	v_lshl_add_u64 v[158:159], v[158:159], 0, s[28:29]
	s_and_b64 vcc, exec, s[8:9]
	s_mov_b64 s[48:49], -1
	s_cbranch_vccnz .LBB0_194
	v_lshlrev_b64 v[160:161], 17, v[152:153]
	v_lshl_add_u64 v[160:161], s[22:23], 0, v[160:161]
	v_lshl_add_u64 v[160:161], v[160:161], 0, v[158:159]
	s_mov_b64 s[48:49], 0

.LBB0_196:
	v_lshlrev_b32_e32 v136, 1, v136
	v_cvt_pk_bf16_f32 v178, v108, v109
	v_cvt_pk_bf16_f32 v179, v110, v111
	v_cvt_pk_bf16_f32 v180, v104, v105
	v_cvt_pk_bf16_f32 v181, v106, v107
	v_lshl_add_u64 v[160:161], v[160:161], 0, v[136:137]
	global_store_dwordx4 v[160:161], v[178:181], off nt
	s_and_b64 vcc, exec, s[8:9]
	s_mov_b64 s[48:49], -1
	s_cbranch_vccnz .LBB0_198
	v_lshlrev_b64 v[160:161], 17, v[154:155]
	v_lshl_add_u64 v[160:161], s[22:23], 0, v[160:161]
	v_lshl_add_u64 v[160:161], v[160:161], 0, v[158:159]
	s_mov_b64 s[48:49], 0

.LBB0_200:
	v_lshlrev_b32_e32 v136, 1, v136
	v_cvt_pk_bf16_f32 v156, v100, v101
	v_cvt_pk_bf16_f32 v157, v102, v103
	v_cvt_pk_bf16_f32 v158, v96, v97
	v_cvt_pk_bf16_f32 v159, v98, v99
	v_lshl_add_u64 v[160:161], v[160:161], 0, v[136:137]
	global_store_dwordx4 v[160:161], v[156:159], off nt
	s_nop 1
	v_add_u32_e32 v156, s12, v164
	v_ashrrev_i32_e32 v157, 31, v156
	v_lshlrev_b64 v[158:159], 7, v[156:157]
	v_lshl_add_u64 v[158:159], v[158:159], 0, s[28:29]
	s_and_b64 vcc, exec, s[8:9]
	s_mov_b64 s[48:49], -1
	s_cbranch_vccnz .LBB0_202
	v_lshlrev_b64 v[160:161], 17, v[152:153]
	v_lshl_add_u64 v[160:161], s[22:23], 0, v[160:161]
	v_lshl_add_u64 v[160:161], v[160:161], 0, v[158:159]
	s_mov_b64 s[48:49], 0

.LBB0_204:
	v_lshlrev_b32_e32 v136, 1, v136
	v_cvt_pk_bf16_f32 v178, v92, v93
	v_cvt_pk_bf16_f32 v179, v94, v95
	v_cvt_pk_bf16_f32 v180, v88, v89
	v_cvt_pk_bf16_f32 v181, v90, v91
	v_lshl_add_u64 v[160:161], v[160:161], 0, v[136:137]
	global_store_dwordx4 v[160:161], v[178:181], off nt
	s_and_b64 vcc, exec, s[8:9]
	s_mov_b64 s[48:49], -1
	s_cbranch_vccnz .LBB0_206
	v_lshlrev_b64 v[160:161], 17, v[154:155]
	v_lshl_add_u64 v[160:161], s[22:23], 0, v[160:161]
	v_lshl_add_u64 v[160:161], v[160:161], 0, v[158:159]
	s_mov_b64 s[48:49], 0

.LBB0_208:
	v_lshlrev_b32_e32 v136, 1, v136
	v_cvt_pk_bf16_f32 v156, v84, v85
	v_cvt_pk_bf16_f32 v157, v86, v87
	v_cvt_pk_bf16_f32 v158, v80, v81
	v_cvt_pk_bf16_f32 v159, v82, v83
	v_lshl_add_u64 v[160:161], v[160:161], 0, v[136:137]
	global_store_dwordx4 v[160:161], v[156:159], off nt
	s_nop 1
	v_add_u32_e32 v156, s12, v165
	v_ashrrev_i32_e32 v157, 31, v156
	v_lshlrev_b64 v[158:159], 7, v[156:157]
	v_lshl_add_u64 v[158:159], v[158:159], 0, s[28:29]
	s_and_b64 vcc, exec, s[8:9]
	s_mov_b64 s[48:49], -1
	s_cbranch_vccnz .LBB0_210
	v_lshlrev_b64 v[160:161], 17, v[152:153]
	v_lshl_add_u64 v[160:161], s[22:23], 0, v[160:161]
	v_lshl_add_u64 v[160:161], v[160:161], 0, v[158:159]
	s_mov_b64 s[48:49], 0

.LBB0_212:
	v_lshlrev_b32_e32 v136, 1, v136
	v_cvt_pk_bf16_f32 v178, v76, v77
	v_cvt_pk_bf16_f32 v179, v78, v79
	v_cvt_pk_bf16_f32 v180, v72, v73
	v_cvt_pk_bf16_f32 v181, v74, v75
	v_lshl_add_u64 v[160:161], v[160:161], 0, v[136:137]
	global_store_dwordx4 v[160:161], v[178:181], off nt
	s_and_b64 vcc, exec, s[8:9]
	s_mov_b64 s[48:49], -1
	s_cbranch_vccnz .LBB0_214
	v_lshlrev_b64 v[160:161], 17, v[154:155]
	v_lshl_add_u64 v[160:161], s[22:23], 0, v[160:161]
	v_lshl_add_u64 v[160:161], v[160:161], 0, v[158:159]
	s_mov_b64 s[48:49], 0

.LBB0_216:
	v_lshlrev_b32_e32 v136, 1, v136
	v_cvt_pk_bf16_f32 v156, v68, v69
	v_cvt_pk_bf16_f32 v157, v70, v71
	v_cvt_pk_bf16_f32 v158, v64, v65
	v_cvt_pk_bf16_f32 v159, v66, v67
	v_lshl_add_u64 v[160:161], v[160:161], 0, v[136:137]
	global_store_dwordx4 v[160:161], v[156:159], off nt
	s_nop 1
	v_add_u32_e32 v156, s12, v166
	v_ashrrev_i32_e32 v157, 31, v156
	v_lshlrev_b64 v[158:159], 7, v[156:157]
	v_lshl_add_u64 v[158:159], v[158:159], 0, s[28:29]
	s_and_b64 vcc, exec, s[8:9]
	s_mov_b64 s[48:49], -1
	s_cbranch_vccnz .LBB0_218
	v_lshlrev_b64 v[160:161], 17, v[152:153]
	v_lshl_add_u64 v[160:161], s[22:23], 0, v[160:161]
	v_lshl_add_u64 v[160:161], v[160:161], 0, v[158:159]
	s_mov_b64 s[48:49], 0

.LBB0_220:
	v_lshlrev_b32_e32 v136, 1, v136
	v_cvt_pk_bf16_f32 v178, v60, v61
	v_cvt_pk_bf16_f32 v179, v62, v63
	v_cvt_pk_bf16_f32 v180, v56, v57
	v_cvt_pk_bf16_f32 v181, v58, v59
	v_lshl_add_u64 v[160:161], v[160:161], 0, v[136:137]
	global_store_dwordx4 v[160:161], v[178:181], off nt
	s_and_b64 vcc, exec, s[8:9]
	s_mov_b64 s[48:49], -1
	s_cbranch_vccnz .LBB0_222
	v_lshlrev_b64 v[160:161], 17, v[154:155]
	v_lshl_add_u64 v[160:161], s[22:23], 0, v[160:161]
	v_lshl_add_u64 v[160:161], v[160:161], 0, v[158:159]
	s_mov_b64 s[48:49], 0

.LBB0_224:
	v_lshlrev_b32_e32 v136, 1, v136
	v_cvt_pk_bf16_f32 v156, v52, v53
	v_cvt_pk_bf16_f32 v157, v54, v55
	v_cvt_pk_bf16_f32 v158, v48, v49
	v_cvt_pk_bf16_f32 v159, v50, v51
	v_lshl_add_u64 v[160:161], v[160:161], 0, v[136:137]
	global_store_dwordx4 v[160:161], v[156:159], off nt
	s_nop 1
	v_add_u32_e32 v156, s12, v167
	v_ashrrev_i32_e32 v157, 31, v156
	v_lshlrev_b64 v[158:159], 7, v[156:157]
	v_lshl_add_u64 v[158:159], v[158:159], 0, s[28:29]
	s_and_b64 vcc, exec, s[8:9]
	s_mov_b64 s[48:49], -1
	s_cbranch_vccnz .LBB0_226
	v_lshlrev_b64 v[160:161], 17, v[152:153]
	v_lshl_add_u64 v[160:161], s[22:23], 0, v[160:161]
	v_lshl_add_u64 v[160:161], v[160:161], 0, v[158:159]
	s_mov_b64 s[48:49], 0

.LBB0_228:
	v_lshlrev_b32_e32 v136, 1, v136
	v_cvt_pk_bf16_f32 v178, v44, v45
	v_cvt_pk_bf16_f32 v179, v46, v47
	v_cvt_pk_bf16_f32 v180, v40, v41
	v_cvt_pk_bf16_f32 v181, v42, v43
	v_lshl_add_u64 v[160:161], v[160:161], 0, v[136:137]
	global_store_dwordx4 v[160:161], v[178:181], off nt
	s_and_b64 vcc, exec, s[8:9]
	s_mov_b64 s[48:49], -1
	s_cbranch_vccnz .LBB0_230
	v_lshlrev_b64 v[160:161], 17, v[154:155]
	v_lshl_add_u64 v[160:161], s[22:23], 0, v[160:161]
	v_lshl_add_u64 v[160:161], v[160:161], 0, v[158:159]
	s_mov_b64 s[48:49], 0

.LBB0_232:
	v_lshlrev_b32_e32 v136, 1, v136
	v_cvt_pk_bf16_f32 v156, v36, v37
	v_cvt_pk_bf16_f32 v157, v38, v39
	v_cvt_pk_bf16_f32 v158, v32, v33
	v_cvt_pk_bf16_f32 v159, v34, v35
	v_lshl_add_u64 v[160:161], v[160:161], 0, v[136:137]
	global_store_dwordx4 v[160:161], v[156:159], off nt
	s_nop 1
	v_add_u32_e32 v156, s12, v168
	v_ashrrev_i32_e32 v157, 31, v156
	v_lshlrev_b64 v[158:159], 7, v[156:157]
	v_lshl_add_u64 v[158:159], v[158:159], 0, s[28:29]
	s_and_b64 vcc, exec, s[8:9]
	s_mov_b64 s[48:49], -1
	s_cbranch_vccnz .LBB0_234
	v_lshlrev_b64 v[160:161], 17, v[152:153]
	v_lshl_add_u64 v[160:161], s[22:23], 0, v[160:161]
	v_lshl_add_u64 v[160:161], v[160:161], 0, v[158:159]
	s_mov_b64 s[48:49], 0

.LBB0_236:
	v_lshlrev_b32_e32 v136, 1, v136
	v_cvt_pk_bf16_f32 v178, v28, v29
	v_cvt_pk_bf16_f32 v179, v30, v31
	v_cvt_pk_bf16_f32 v180, v24, v25
	v_cvt_pk_bf16_f32 v181, v26, v27
	v_lshl_add_u64 v[160:161], v[160:161], 0, v[136:137]
	global_store_dwordx4 v[160:161], v[178:181], off nt
	s_and_b64 vcc, exec, s[8:9]
	s_mov_b64 s[48:49], -1
	s_cbranch_vccnz .LBB0_238
	v_lshlrev_b64 v[160:161], 17, v[154:155]
	v_lshl_add_u64 v[160:161], s[22:23], 0, v[160:161]
	v_lshl_add_u64 v[160:161], v[160:161], 0, v[158:159]
	s_mov_b64 s[48:49], 0

.LBB0_240:
	v_lshlrev_b32_e32 v136, 1, v136
	v_cvt_pk_bf16_f32 v156, v20, v21
	v_cvt_pk_bf16_f32 v157, v22, v23
	v_cvt_pk_bf16_f32 v158, v16, v17
	v_cvt_pk_bf16_f32 v159, v18, v19
	v_lshl_add_u64 v[160:161], v[160:161], 0, v[136:137]
	global_store_dwordx4 v[160:161], v[156:159], off nt
	v_add_u32_e32 v160, s12, v169
	v_ashrrev_i32_e32 v161, 31, v160
	v_lshlrev_b64 v[156:157], 7, v[160:161]
	v_lshl_add_u64 v[156:157], v[156:157], 0, s[28:29]
	s_and_b64 vcc, exec, s[8:9]
	s_mov_b64 s[48:49], -1
	s_cbranch_vccnz .LBB0_242
	v_lshlrev_b64 v[152:153], 17, v[152:153]
	v_lshl_add_u64 v[152:153], s[22:23], 0, v[152:153]
	v_lshl_add_u64 v[158:159], v[152:153], 0, v[156:157]
	s_mov_b64 s[48:49], 0

.LBB0_244:
	v_lshlrev_b32_e32 v136, 1, v136
	v_cvt_pk_bf16_f32 v176, v12, v13
	v_cvt_pk_bf16_f32 v177, v14, v15
	v_cvt_pk_bf16_f32 v178, v8, v9
	v_cvt_pk_bf16_f32 v179, v10, v11
	v_lshl_add_u64 v[158:159], v[158:159], 0, v[136:137]
	global_store_dwordx4 v[158:159], v[176:179], off nt
	s_and_b64 vcc, exec, s[8:9]
	s_mov_b64 s[8:9], -1
	s_cbranch_vccnz .LBB0_246
	v_lshlrev_b64 v[154:155], 17, v[154:155]
	v_lshl_add_u64 v[154:155], s[22:23], 0, v[154:155]
	v_lshl_add_u64 v[158:159], v[154:155], 0, v[156:157]
	s_mov_b64 s[8:9], 0

.LBB0_248:
	v_lshlrev_b32_e32 v136, 1, v136
	v_cvt_pk_bf16_f32 v152, v4, v5
	v_cvt_pk_bf16_f32 v153, v6, v7
	v_cvt_pk_bf16_f32 v154, v0, v1
	v_cvt_pk_bf16_f32 v155, v2, v3
	v_lshl_add_u64 v[156:157], v[158:159], 0, v[136:137]
	global_store_dwordx4 v[156:157], v[152:155], off nt
	s_branch .LBB0_289
.LBB0_249:
	s_cbranch_execz .LBB0_289
	s_cmp_gt_i32 s46, 45
	s_mov_b64 s[8:9], -1
	s_cbranch_scc0 .LBB0_256
	s_cmpk_lt_u32 s46, 0x4e
	s_cbranch_scc1 .LBB0_253
	s_lshl_b32 s8, s44, 8
	v_add_u32_e32 v152, s8, v139
	v_ashrrev_i32_e32 v153, 31, v152
	v_lshlrev_b64 v[152:153], 9, v[152:153]
	v_lshl_add_u64 v[152:153], v[142:143], 0, v[152:153]
	global_store_dwordx4 v[152:153], v[124:127], off nt
	global_store_dwordx4 v[152:153], v[120:123], off offset:16 nt
	v_add_u32_e32 v152, s8, v163
	v_ashrrev_i32_e32 v153, 31, v152
	v_lshlrev_b64 v[152:153], 9, v[152:153]
	v_lshl_add_u64 v[152:153], v[142:143], 0, v[152:153]
	global_store_dwordx4 v[152:153], v[108:111], off nt
	global_store_dwordx4 v[152:153], v[104:107], off offset:16 nt
	v_add_u32_e32 v152, s8, v164
	v_ashrrev_i32_e32 v153, 31, v152
	v_lshlrev_b64 v[152:153], 9, v[152:153]
	v_lshl_add_u64 v[152:153], v[142:143], 0, v[152:153]
	global_store_dwordx4 v[152:153], v[92:95], off nt
	global_store_dwordx4 v[152:153], v[88:91], off offset:16 nt
	v_add_u32_e32 v152, s8, v165
	v_ashrrev_i32_e32 v153, 31, v152
	v_lshlrev_b64 v[152:153], 9, v[152:153]
	v_lshl_add_u64 v[152:153], v[142:143], 0, v[152:153]
	global_store_dwordx4 v[152:153], v[76:79], off nt
	global_store_dwordx4 v[152:153], v[72:75], off offset:16 nt
	v_add_u32_e32 v152, s8, v166
	v_ashrrev_i32_e32 v153, 31, v152
	v_lshlrev_b64 v[152:153], 9, v[152:153]
	v_lshl_add_u64 v[152:153], v[142:143], 0, v[152:153]
	global_store_dwordx4 v[152:153], v[60:63], off nt
	global_store_dwordx4 v[152:153], v[56:59], off offset:16 nt
	v_add_u32_e32 v152, s8, v167
	v_ashrrev_i32_e32 v153, 31, v152
	v_lshlrev_b64 v[152:153], 9, v[152:153]
	v_lshl_add_u64 v[152:153], v[142:143], 0, v[152:153]
	global_store_dwordx4 v[152:153], v[44:47], off nt
	global_store_dwordx4 v[152:153], v[40:43], off offset:16 nt
	v_add_u32_e32 v152, s8, v168
	v_ashrrev_i32_e32 v153, 31, v152
	v_lshlrev_b64 v[152:153], 9, v[152:153]
	v_lshl_add_u64 v[152:153], v[142:143], 0, v[152:153]
	global_store_dwordx4 v[152:153], v[28:31], off nt
	global_store_dwordx4 v[152:153], v[24:27], off offset:16 nt
	v_add_u32_e32 v152, s8, v169
	v_ashrrev_i32_e32 v153, 31, v152
	v_lshlrev_b64 v[152:153], 9, v[152:153]
	v_lshl_add_u64 v[152:153], v[142:143], 0, v[152:153]
	global_store_dwordx4 v[152:153], v[12:15], off nt
	global_store_dwordx4 v[152:153], v[8:11], off offset:16 nt
	s_mov_b64 s[8:9], 0
.LBB0_253:
	s_andn2_b64 vcc, exec, s[8:9]
	s_cbranch_vccnz .LBB0_255
	v_mul_f32_e32 v154, 0xbfb8aa3b, v125
	v_exp_f32_e32 v154, v154
	s_lshl_b32 s8, s44, 8
	v_add_u32_e32 v152, s8, v139
	v_ashrrev_i32_e32 v153, 31, v152
	v_mul_f32_e32 v136, 0xbfb8aa3b, v124
	v_lshlrev_b64 v[156:157], 14, v[152:153]
	v_add_f32_e32 v152, 1.0, v154
	v_mul_f32_e32 v153, 0xbfb8aa3b, v126
	v_mul_f32_e32 v154, 0xbfb8aa3b, v127
	v_mul_f32_e32 v155, 0xbfb8aa3b, v120
	v_mul_f32_e32 v158, 0xbfb8aa3b, v121
	v_mul_f32_e32 v159, 0xbfb8aa3b, v122
	v_mul_f32_e32 v160, 0xbfb8aa3b, v123
	v_exp_f32_e32 v136, v136
	v_exp_f32_e32 v153, v153
	v_exp_f32_e32 v154, v154
	v_exp_f32_e32 v155, v155
	v_exp_f32_e32 v158, v158
	v_exp_f32_e32 v159, v159
	v_exp_f32_e32 v160, v160
	v_add_f32_e32 v136, 1.0, v136
	v_add_f32_e32 v153, 1.0, v153
	v_add_f32_e32 v154, 1.0, v154
	v_add_f32_e32 v155, 1.0, v155
	v_add_f32_e32 v158, 1.0, v158
	v_add_f32_e32 v159, 1.0, v159
	v_add_f32_e32 v160, 1.0, v160
	v_rcp_f32_e32 v136, v136
	v_rcp_f32_e32 v152, v152
	v_rcp_f32_e32 v153, v153
	v_rcp_f32_e32 v154, v154
	v_rcp_f32_e32 v155, v155
	v_rcp_f32_e32 v158, v158
	v_rcp_f32_e32 v159, v159
	v_rcp_f32_e32 v160, v160
	v_lshl_add_u64 v[156:157], s[18:19], 0, v[156:157]
	s_lshl_b32 s12, s46, 9
	v_lshl_add_u64 v[156:157], v[156:157], 0, s[12:13]
	v_cvt_pk_bf16_f32 v152, v136, v152
	v_cvt_pk_bf16_f32 v153, v153, v154
	v_cvt_pk_bf16_f32 v154, v155, v158
	v_cvt_pk_bf16_f32 v155, v159, v160
	v_lshl_add_u64 v[158:159], v[156:157], 0, s[34:35]
	v_lshlrev_b32_e32 v136, 1, v138
	v_lshl_add_u64 v[156:157], v[158:159], 0, v[136:137]
	global_store_dwordx4 v[156:157], v[152:155], off nt
	s_nop 1
	v_mul_f32_e32 v154, 0xbfb8aa3b, v118
	v_exp_f32_e32 v154, v154
	v_mul_f32_e32 v155, 0xbfb8aa3b, v119
	v_exp_f32_e32 v155, v155
	v_mul_f32_e32 v157, 0xbfb8aa3b, v113
	v_add_f32_e32 v154, 1.0, v154
	v_rcp_f32_e32 v156, v154
	v_add_f32_e32 v154, 1.0, v155
	v_mul_f32_e32 v155, 0xbfb8aa3b, v112
	v_exp_f32_e32 v155, v155
	v_exp_f32_e32 v157, v157
	v_mul_f32_e32 v152, 0xbfb8aa3b, v116
	v_mul_f32_e32 v153, 0xbfb8aa3b, v117
	v_rcp_f32_e32 v160, v154
	v_add_f32_e32 v154, 1.0, v155
	v_mul_f32_e32 v155, 0xbfb8aa3b, v114
	v_exp_f32_e32 v152, v152
	v_exp_f32_e32 v153, v153
	v_rcp_f32_e32 v161, v154
	v_add_f32_e32 v154, 1.0, v157
	v_exp_f32_e32 v155, v155
	v_mul_f32_e32 v157, 0xbfb8aa3b, v115
	v_exp_f32_e32 v157, v157
	v_add_f32_e32 v152, 1.0, v152
	v_add_f32_e32 v153, 1.0, v153
	v_rcp_f32_e32 v174, v154
	v_add_f32_e32 v154, 1.0, v155
	v_rcp_f32_e32 v152, v152
	v_rcp_f32_e32 v153, v153
	v_rcp_f32_e32 v175, v154
	v_add_f32_e32 v154, 1.0, v157
	v_rcp_f32_e32 v157, v154
	v_cvt_pk_bf16_f32 v154, v152, v153
	v_lshlrev_b32_e32 v152, 1, v140
	v_mov_b32_e32 v153, v137
	v_cvt_pk_bf16_f32 v155, v156, v160
	v_cvt_pk_bf16_f32 v156, v161, v174
	v_cvt_pk_bf16_f32 v157, v175, v157
	v_lshl_add_u64 v[158:159], v[158:159], 0, v[152:153]
	global_store_dwordx4 v[158:159], v[154:157], off nt
	s_nop 1
	v_mul_f32_e32 v156, 0xbfb8aa3b, v108
	v_mul_f32_e32 v157, 0xbfb8aa3b, v109
	v_exp_f32_e32 v156, v156
	v_exp_f32_e32 v157, v157
	v_add_u32_e32 v154, s8, v163
	v_ashrrev_i32_e32 v155, 31, v154
	v_lshlrev_b64 v[158:159], 14, v[154:155]
	v_add_f32_e32 v154, 1.0, v156
	v_add_f32_e32 v155, 1.0, v157
	v_mul_f32_e32 v156, 0xbfb8aa3b, v110
	v_mul_f32_e32 v157, 0xbfb8aa3b, v111
	v_mul_f32_e32 v160, 0xbfb8aa3b, v104
	v_mul_f32_e32 v161, 0xbfb8aa3b, v105
	v_mul_f32_e32 v174, 0xbfb8aa3b, v106
	v_mul_f32_e32 v175, 0xbfb8aa3b, v107
	v_exp_f32_e32 v156, v156
	v_exp_f32_e32 v157, v157
	v_exp_f32_e32 v160, v160
	v_exp_f32_e32 v161, v161
	v_exp_f32_e32 v174, v174
	v_exp_f32_e32 v175, v175
	v_add_f32_e32 v156, 1.0, v156
	v_add_f32_e32 v157, 1.0, v157
	v_add_f32_e32 v160, 1.0, v160
	v_add_f32_e32 v161, 1.0, v161
	v_add_f32_e32 v174, 1.0, v174
	v_add_f32_e32 v175, 1.0, v175
	v_rcp_f32_e32 v154, v154
	v_rcp_f32_e32 v155, v155
	v_rcp_f32_e32 v156, v156
	v_rcp_f32_e32 v157, v157
	v_rcp_f32_e32 v160, v160
	v_rcp_f32_e32 v161, v161
	v_rcp_f32_e32 v174, v174
	v_rcp_f32_e32 v175, v175
	v_lshl_add_u64 v[158:159], s[18:19], 0, v[158:159]
	v_lshl_add_u64 v[158:159], v[158:159], 0, s[12:13]
	v_lshl_add_u64 v[158:159], v[158:159], 0, s[34:35]
	v_cvt_pk_bf16_f32 v154, v154, v155
	v_cvt_pk_bf16_f32 v155, v156, v157
	v_cvt_pk_bf16_f32 v156, v160, v161
	v_cvt_pk_bf16_f32 v157, v174, v175
	v_lshl_add_u64 v[160:161], v[158:159], 0, v[136:137]
	global_store_dwordx4 v[160:161], v[154:157], off nt
	s_nop 1
	v_mul_f32_e32 v154, 0xbfb8aa3b, v100
	v_mul_f32_e32 v155, 0xbfb8aa3b, v101
	v_mul_f32_e32 v156, 0xbfb8aa3b, v102
	v_mul_f32_e32 v157, 0xbfb8aa3b, v103
	v_mul_f32_e32 v160, 0xbfb8aa3b, v96
	v_mul_f32_e32 v161, 0xbfb8aa3b, v97
	v_mul_f32_e32 v174, 0xbfb8aa3b, v98
	v_mul_f32_e32 v175, 0xbfb8aa3b, v99
	v_exp_f32_e32 v154, v154
	v_exp_f32_e32 v155, v155
	v_exp_f32_e32 v156, v156
	v_exp_f32_e32 v157, v157
	v_exp_f32_e32 v160, v160
	v_exp_f32_e32 v161, v161
	v_exp_f32_e32 v174, v174
	v_exp_f32_e32 v175, v175
	v_add_f32_e32 v154, 1.0, v154
	v_add_f32_e32 v155, 1.0, v155
	v_add_f32_e32 v156, 1.0, v156
	v_add_f32_e32 v157, 1.0, v157
	v_add_f32_e32 v160, 1.0, v160
	v_add_f32_e32 v161, 1.0, v161
	v_add_f32_e32 v174, 1.0, v174
	v_add_f32_e32 v175, 1.0, v175
	v_rcp_f32_e32 v154, v154
	v_rcp_f32_e32 v155, v155
	v_rcp_f32_e32 v156, v156
	v_rcp_f32_e32 v157, v157
	v_rcp_f32_e32 v160, v160
	v_rcp_f32_e32 v161, v161
	v_rcp_f32_e32 v174, v174
	v_rcp_f32_e32 v175, v175
	v_cvt_pk_bf16_f32 v154, v154, v155
	v_cvt_pk_bf16_f32 v155, v156, v157
	v_cvt_pk_bf16_f32 v156, v160, v161
	v_cvt_pk_bf16_f32 v157, v174, v175
	v_lshl_add_u64 v[158:159], v[158:159], 0, v[152:153]
	global_store_dwordx4 v[158:159], v[154:157], off nt
	s_nop 1
	v_mul_f32_e32 v156, 0xbfb8aa3b, v92
	v_mul_f32_e32 v157, 0xbfb8aa3b, v93
	v_exp_f32_e32 v156, v156
	v_exp_f32_e32 v157, v157
	v_add_u32_e32 v154, s8, v164
	v_ashrrev_i32_e32 v155, 31, v154
	v_lshlrev_b64 v[158:159], 14, v[154:155]
	v_add_f32_e32 v154, 1.0, v156
	v_add_f32_e32 v155, 1.0, v157
	v_mul_f32_e32 v156, 0xbfb8aa3b, v94
	v_mul_f32_e32 v157, 0xbfb8aa3b, v95
	v_mul_f32_e32 v160, 0xbfb8aa3b, v88
	v_mul_f32_e32 v161, 0xbfb8aa3b, v89
	v_mul_f32_e32 v174, 0xbfb8aa3b, v90
	v_mul_f32_e32 v175, 0xbfb8aa3b, v91
	v_exp_f32_e32 v156, v156
	v_exp_f32_e32 v157, v157
	v_exp_f32_e32 v160, v160
	v_exp_f32_e32 v161, v161
	v_exp_f32_e32 v174, v174
	v_exp_f32_e32 v175, v175
	v_add_f32_e32 v156, 1.0, v156
	v_add_f32_e32 v157, 1.0, v157
	v_add_f32_e32 v160, 1.0, v160
	v_add_f32_e32 v161, 1.0, v161
	v_add_f32_e32 v174, 1.0, v174
	v_add_f32_e32 v175, 1.0, v175
	v_rcp_f32_e32 v154, v154
	v_rcp_f32_e32 v155, v155
	v_rcp_f32_e32 v156, v156
	v_rcp_f32_e32 v157, v157
	v_rcp_f32_e32 v160, v160
	v_rcp_f32_e32 v161, v161
	v_rcp_f32_e32 v174, v174
	v_rcp_f32_e32 v175, v175
	v_lshl_add_u64 v[158:159], s[18:19], 0, v[158:159]
	v_lshl_add_u64 v[158:159], v[158:159], 0, s[12:13]
	v_lshl_add_u64 v[158:159], v[158:159], 0, s[34:35]
	v_cvt_pk_bf16_f32 v154, v154, v155
	v_cvt_pk_bf16_f32 v155, v156, v157
	v_cvt_pk_bf16_f32 v156, v160, v161
	v_cvt_pk_bf16_f32 v157, v174, v175
	v_lshl_add_u64 v[160:161], v[158:159], 0, v[136:137]
	global_store_dwordx4 v[160:161], v[154:157], off nt
	s_nop 1
	v_mul_f32_e32 v154, 0xbfb8aa3b, v84
	v_mul_f32_e32 v155, 0xbfb8aa3b, v85
	v_mul_f32_e32 v156, 0xbfb8aa3b, v86
	v_mul_f32_e32 v157, 0xbfb8aa3b, v87
	v_mul_f32_e32 v160, 0xbfb8aa3b, v80
	v_mul_f32_e32 v161, 0xbfb8aa3b, v81
	v_mul_f32_e32 v174, 0xbfb8aa3b, v82
	v_mul_f32_e32 v175, 0xbfb8aa3b, v83
	v_exp_f32_e32 v154, v154
	v_exp_f32_e32 v155, v155
	v_exp_f32_e32 v156, v156
	v_exp_f32_e32 v157, v157
	v_exp_f32_e32 v160, v160
	v_exp_f32_e32 v161, v161
	v_exp_f32_e32 v174, v174
	v_exp_f32_e32 v175, v175
	v_add_f32_e32 v154, 1.0, v154
	v_add_f32_e32 v155, 1.0, v155
	v_add_f32_e32 v156, 1.0, v156
	v_add_f32_e32 v157, 1.0, v157
	v_add_f32_e32 v160, 1.0, v160
	v_add_f32_e32 v161, 1.0, v161
	v_add_f32_e32 v174, 1.0, v174
	v_add_f32_e32 v175, 1.0, v175
	v_rcp_f32_e32 v154, v154
	v_rcp_f32_e32 v155, v155
	v_rcp_f32_e32 v156, v156
	v_rcp_f32_e32 v157, v157
	v_rcp_f32_e32 v160, v160
	v_rcp_f32_e32 v161, v161
	v_rcp_f32_e32 v174, v174
	v_rcp_f32_e32 v175, v175
	v_cvt_pk_bf16_f32 v154, v154, v155
	v_cvt_pk_bf16_f32 v155, v156, v157
	v_cvt_pk_bf16_f32 v156, v160, v161
	v_cvt_pk_bf16_f32 v157, v174, v175
	v_lshl_add_u64 v[158:159], v[158:159], 0, v[152:153]
	global_store_dwordx4 v[158:159], v[154:157], off nt
	s_nop 1
	v_mul_f32_e32 v156, 0xbfb8aa3b, v76
	v_mul_f32_e32 v157, 0xbfb8aa3b, v77
	v_exp_f32_e32 v156, v156
	v_exp_f32_e32 v157, v157
	v_add_u32_e32 v154, s8, v165
	v_ashrrev_i32_e32 v155, 31, v154
	v_lshlrev_b64 v[158:159], 14, v[154:155]
	v_add_f32_e32 v154, 1.0, v156
	v_add_f32_e32 v155, 1.0, v157
	v_mul_f32_e32 v156, 0xbfb8aa3b, v78
	v_mul_f32_e32 v157, 0xbfb8aa3b, v79
	v_mul_f32_e32 v160, 0xbfb8aa3b, v72
	v_mul_f32_e32 v161, 0xbfb8aa3b, v73
	v_mul_f32_e32 v174, 0xbfb8aa3b, v74
	v_mul_f32_e32 v175, 0xbfb8aa3b, v75
	v_exp_f32_e32 v156, v156
	v_exp_f32_e32 v157, v157
	v_exp_f32_e32 v160, v160
	v_exp_f32_e32 v161, v161
	v_exp_f32_e32 v174, v174
	v_exp_f32_e32 v175, v175
	v_add_f32_e32 v156, 1.0, v156
	v_add_f32_e32 v157, 1.0, v157
	v_add_f32_e32 v160, 1.0, v160
	v_add_f32_e32 v161, 1.0, v161
	v_add_f32_e32 v174, 1.0, v174
	v_add_f32_e32 v175, 1.0, v175
	v_rcp_f32_e32 v154, v154
	v_rcp_f32_e32 v155, v155
	v_rcp_f32_e32 v156, v156
	v_rcp_f32_e32 v157, v157
	v_rcp_f32_e32 v160, v160
	v_rcp_f32_e32 v161, v161
	v_rcp_f32_e32 v174, v174
	v_rcp_f32_e32 v175, v175
	v_lshl_add_u64 v[158:159], s[18:19], 0, v[158:159]
	v_lshl_add_u64 v[158:159], v[158:159], 0, s[12:13]
	v_lshl_add_u64 v[158:159], v[158:159], 0, s[34:35]
	v_cvt_pk_bf16_f32 v154, v154, v155
	v_cvt_pk_bf16_f32 v155, v156, v157
	v_cvt_pk_bf16_f32 v156, v160, v161
	v_cvt_pk_bf16_f32 v157, v174, v175
	v_lshl_add_u64 v[160:161], v[158:159], 0, v[136:137]
	global_store_dwordx4 v[160:161], v[154:157], off nt
	s_nop 1
	v_mul_f32_e32 v154, 0xbfb8aa3b, v68
	v_mul_f32_e32 v155, 0xbfb8aa3b, v69
	v_mul_f32_e32 v156, 0xbfb8aa3b, v70
	v_mul_f32_e32 v157, 0xbfb8aa3b, v71
	v_mul_f32_e32 v160, 0xbfb8aa3b, v64
	v_mul_f32_e32 v161, 0xbfb8aa3b, v65
	v_mul_f32_e32 v174, 0xbfb8aa3b, v66
	v_mul_f32_e32 v175, 0xbfb8aa3b, v67
	v_exp_f32_e32 v154, v154
	v_exp_f32_e32 v155, v155
	v_exp_f32_e32 v156, v156
	v_exp_f32_e32 v157, v157
	v_exp_f32_e32 v160, v160
	v_exp_f32_e32 v161, v161
	v_exp_f32_e32 v174, v174
	v_exp_f32_e32 v175, v175
	v_add_f32_e32 v154, 1.0, v154
	v_add_f32_e32 v155, 1.0, v155
	v_add_f32_e32 v156, 1.0, v156
	v_add_f32_e32 v157, 1.0, v157
	v_add_f32_e32 v160, 1.0, v160
	v_add_f32_e32 v161, 1.0, v161
	v_add_f32_e32 v174, 1.0, v174
	v_add_f32_e32 v175, 1.0, v175
	v_rcp_f32_e32 v154, v154
	v_rcp_f32_e32 v155, v155
	v_rcp_f32_e32 v156, v156
	v_rcp_f32_e32 v157, v157
	v_rcp_f32_e32 v160, v160
	v_rcp_f32_e32 v161, v161
	v_rcp_f32_e32 v174, v174
	v_rcp_f32_e32 v175, v175
	v_cvt_pk_bf16_f32 v154, v154, v155
	v_cvt_pk_bf16_f32 v155, v156, v157
	v_cvt_pk_bf16_f32 v156, v160, v161
	v_cvt_pk_bf16_f32 v157, v174, v175
	v_lshl_add_u64 v[158:159], v[158:159], 0, v[152:153]
	global_store_dwordx4 v[158:159], v[154:157], off nt
	s_nop 1
	v_mul_f32_e32 v156, 0xbfb8aa3b, v60
	v_mul_f32_e32 v157, 0xbfb8aa3b, v61
	v_exp_f32_e32 v156, v156
	v_exp_f32_e32 v157, v157
	v_add_u32_e32 v154, s8, v166
	v_ashrrev_i32_e32 v155, 31, v154
	v_lshlrev_b64 v[158:159], 14, v[154:155]
	v_add_f32_e32 v154, 1.0, v156
	v_add_f32_e32 v155, 1.0, v157
	v_mul_f32_e32 v156, 0xbfb8aa3b, v62
	v_mul_f32_e32 v157, 0xbfb8aa3b, v63
	v_mul_f32_e32 v160, 0xbfb8aa3b, v56
	v_mul_f32_e32 v161, 0xbfb8aa3b, v57
	v_mul_f32_e32 v174, 0xbfb8aa3b, v58
	v_mul_f32_e32 v175, 0xbfb8aa3b, v59
	v_exp_f32_e32 v156, v156
	v_exp_f32_e32 v157, v157
	v_exp_f32_e32 v160, v160
	v_exp_f32_e32 v161, v161
	v_exp_f32_e32 v174, v174
	v_exp_f32_e32 v175, v175
	v_add_f32_e32 v156, 1.0, v156
	v_add_f32_e32 v157, 1.0, v157
	v_add_f32_e32 v160, 1.0, v160
	v_add_f32_e32 v161, 1.0, v161
	v_add_f32_e32 v174, 1.0, v174
	v_add_f32_e32 v175, 1.0, v175
	v_rcp_f32_e32 v154, v154
	v_rcp_f32_e32 v155, v155
	v_rcp_f32_e32 v156, v156
	v_rcp_f32_e32 v157, v157
	v_rcp_f32_e32 v160, v160
	v_rcp_f32_e32 v161, v161
	v_rcp_f32_e32 v174, v174
	v_rcp_f32_e32 v175, v175
	v_lshl_add_u64 v[158:159], s[18:19], 0, v[158:159]
	v_lshl_add_u64 v[158:159], v[158:159], 0, s[12:13]
	v_lshl_add_u64 v[158:159], v[158:159], 0, s[34:35]
	v_cvt_pk_bf16_f32 v154, v154, v155
	v_cvt_pk_bf16_f32 v155, v156, v157
	v_cvt_pk_bf16_f32 v156, v160, v161
	v_cvt_pk_bf16_f32 v157, v174, v175
	v_lshl_add_u64 v[160:161], v[158:159], 0, v[136:137]
	global_store_dwordx4 v[160:161], v[154:157], off nt
	s_nop 1
	v_mul_f32_e32 v154, 0xbfb8aa3b, v52
	v_mul_f32_e32 v155, 0xbfb8aa3b, v53
	v_mul_f32_e32 v156, 0xbfb8aa3b, v54
	v_mul_f32_e32 v157, 0xbfb8aa3b, v55
	v_mul_f32_e32 v160, 0xbfb8aa3b, v48
	v_mul_f32_e32 v161, 0xbfb8aa3b, v49
	v_mul_f32_e32 v174, 0xbfb8aa3b, v50
	v_mul_f32_e32 v175, 0xbfb8aa3b, v51
	v_exp_f32_e32 v154, v154
	v_exp_f32_e32 v155, v155
	v_exp_f32_e32 v156, v156
	v_exp_f32_e32 v157, v157
	v_exp_f32_e32 v160, v160
	v_exp_f32_e32 v161, v161
	v_exp_f32_e32 v174, v174
	v_exp_f32_e32 v175, v175
	v_add_f32_e32 v154, 1.0, v154
	v_add_f32_e32 v155, 1.0, v155
	v_add_f32_e32 v156, 1.0, v156
	v_add_f32_e32 v157, 1.0, v157
	v_add_f32_e32 v160, 1.0, v160
	v_add_f32_e32 v161, 1.0, v161
	v_add_f32_e32 v174, 1.0, v174
	v_add_f32_e32 v175, 1.0, v175
	v_rcp_f32_e32 v154, v154
	v_rcp_f32_e32 v155, v155
	v_rcp_f32_e32 v156, v156
	v_rcp_f32_e32 v157, v157
	v_rcp_f32_e32 v160, v160
	v_rcp_f32_e32 v161, v161
	v_rcp_f32_e32 v174, v174
	v_rcp_f32_e32 v175, v175
	v_cvt_pk_bf16_f32 v154, v154, v155
	v_cvt_pk_bf16_f32 v155, v156, v157
	v_cvt_pk_bf16_f32 v156, v160, v161
	v_cvt_pk_bf16_f32 v157, v174, v175
	v_lshl_add_u64 v[158:159], v[158:159], 0, v[152:153]
	global_store_dwordx4 v[158:159], v[154:157], off nt
	s_nop 1
	v_mul_f32_e32 v156, 0xbfb8aa3b, v44
	v_mul_f32_e32 v157, 0xbfb8aa3b, v45
	v_exp_f32_e32 v156, v156
	v_exp_f32_e32 v157, v157
	v_add_u32_e32 v154, s8, v167
	v_ashrrev_i32_e32 v155, 31, v154
	v_lshlrev_b64 v[158:159], 14, v[154:155]
	v_add_f32_e32 v154, 1.0, v156
	v_add_f32_e32 v155, 1.0, v157
	v_mul_f32_e32 v156, 0xbfb8aa3b, v46
	v_mul_f32_e32 v157, 0xbfb8aa3b, v47
	v_mul_f32_e32 v160, 0xbfb8aa3b, v40
	v_mul_f32_e32 v161, 0xbfb8aa3b, v41
	v_mul_f32_e32 v174, 0xbfb8aa3b, v42
	v_mul_f32_e32 v175, 0xbfb8aa3b, v43
	v_exp_f32_e32 v156, v156
	v_exp_f32_e32 v157, v157
	v_exp_f32_e32 v160, v160
	v_exp_f32_e32 v161, v161
	v_exp_f32_e32 v174, v174
	v_exp_f32_e32 v175, v175
	v_add_f32_e32 v156, 1.0, v156
	v_add_f32_e32 v157, 1.0, v157
	v_add_f32_e32 v160, 1.0, v160
	v_add_f32_e32 v161, 1.0, v161
	v_add_f32_e32 v174, 1.0, v174
	v_add_f32_e32 v175, 1.0, v175
	v_rcp_f32_e32 v154, v154
	v_rcp_f32_e32 v155, v155
	v_rcp_f32_e32 v156, v156
	v_rcp_f32_e32 v157, v157
	v_rcp_f32_e32 v160, v160
	v_rcp_f32_e32 v161, v161
	v_rcp_f32_e32 v174, v174
	v_rcp_f32_e32 v175, v175
	v_lshl_add_u64 v[158:159], s[18:19], 0, v[158:159]
	v_lshl_add_u64 v[158:159], v[158:159], 0, s[12:13]
	v_lshl_add_u64 v[158:159], v[158:159], 0, s[34:35]
	v_cvt_pk_bf16_f32 v154, v154, v155
	v_cvt_pk_bf16_f32 v155, v156, v157
	v_cvt_pk_bf16_f32 v156, v160, v161
	v_cvt_pk_bf16_f32 v157, v174, v175
	v_lshl_add_u64 v[160:161], v[158:159], 0, v[136:137]
	global_store_dwordx4 v[160:161], v[154:157], off nt
	s_nop 1
	v_mul_f32_e32 v154, 0xbfb8aa3b, v36
	v_mul_f32_e32 v155, 0xbfb8aa3b, v37
	v_mul_f32_e32 v156, 0xbfb8aa3b, v38
	v_mul_f32_e32 v157, 0xbfb8aa3b, v39
	v_mul_f32_e32 v160, 0xbfb8aa3b, v32
	v_mul_f32_e32 v161, 0xbfb8aa3b, v33
	v_mul_f32_e32 v174, 0xbfb8aa3b, v34
	v_mul_f32_e32 v175, 0xbfb8aa3b, v35
	v_exp_f32_e32 v154, v154
	v_exp_f32_e32 v155, v155
	v_exp_f32_e32 v156, v156
	v_exp_f32_e32 v157, v157
	v_exp_f32_e32 v160, v160
	v_exp_f32_e32 v161, v161
	v_exp_f32_e32 v174, v174
	v_exp_f32_e32 v175, v175
	v_add_f32_e32 v154, 1.0, v154
	v_add_f32_e32 v155, 1.0, v155
	v_add_f32_e32 v156, 1.0, v156
	v_add_f32_e32 v157, 1.0, v157
	v_add_f32_e32 v160, 1.0, v160
	v_add_f32_e32 v161, 1.0, v161
	v_add_f32_e32 v174, 1.0, v174
	v_add_f32_e32 v175, 1.0, v175
	v_rcp_f32_e32 v154, v154
	v_rcp_f32_e32 v155, v155
	v_rcp_f32_e32 v156, v156
	v_rcp_f32_e32 v157, v157
	v_rcp_f32_e32 v160, v160
	v_rcp_f32_e32 v161, v161
	v_rcp_f32_e32 v174, v174
	v_rcp_f32_e32 v175, v175
	v_cvt_pk_bf16_f32 v154, v154, v155
	v_cvt_pk_bf16_f32 v155, v156, v157
	v_cvt_pk_bf16_f32 v156, v160, v161
	v_cvt_pk_bf16_f32 v157, v174, v175
	v_lshl_add_u64 v[158:159], v[158:159], 0, v[152:153]
	global_store_dwordx4 v[158:159], v[154:157], off nt
	s_nop 1
	v_mul_f32_e32 v156, 0xbfb8aa3b, v28
	v_mul_f32_e32 v157, 0xbfb8aa3b, v29
	v_exp_f32_e32 v156, v156
	v_exp_f32_e32 v157, v157
	v_add_u32_e32 v154, s8, v168
	v_ashrrev_i32_e32 v155, 31, v154
	v_lshlrev_b64 v[158:159], 14, v[154:155]
	v_add_f32_e32 v154, 1.0, v156
	v_add_f32_e32 v155, 1.0, v157
	v_mul_f32_e32 v156, 0xbfb8aa3b, v30
	v_mul_f32_e32 v157, 0xbfb8aa3b, v31
	v_mul_f32_e32 v160, 0xbfb8aa3b, v24
	v_mul_f32_e32 v161, 0xbfb8aa3b, v25
	v_mul_f32_e32 v174, 0xbfb8aa3b, v26
	v_mul_f32_e32 v175, 0xbfb8aa3b, v27
	v_exp_f32_e32 v156, v156
	v_exp_f32_e32 v157, v157
	v_exp_f32_e32 v160, v160
	v_exp_f32_e32 v161, v161
	v_exp_f32_e32 v174, v174
	v_exp_f32_e32 v175, v175
	v_add_f32_e32 v156, 1.0, v156
	v_add_f32_e32 v157, 1.0, v157
	v_add_f32_e32 v160, 1.0, v160
	v_add_f32_e32 v161, 1.0, v161
	v_add_f32_e32 v174, 1.0, v174
	v_add_f32_e32 v175, 1.0, v175
	v_rcp_f32_e32 v154, v154
	v_rcp_f32_e32 v155, v155
	v_rcp_f32_e32 v156, v156
	v_rcp_f32_e32 v157, v157
	v_rcp_f32_e32 v160, v160
	v_rcp_f32_e32 v161, v161
	v_rcp_f32_e32 v174, v174
	v_rcp_f32_e32 v175, v175
	v_lshl_add_u64 v[158:159], s[18:19], 0, v[158:159]
	v_lshl_add_u64 v[158:159], v[158:159], 0, s[12:13]
	v_lshl_add_u64 v[158:159], v[158:159], 0, s[34:35]
	v_cvt_pk_bf16_f32 v154, v154, v155
	v_cvt_pk_bf16_f32 v155, v156, v157
	v_cvt_pk_bf16_f32 v156, v160, v161
	v_cvt_pk_bf16_f32 v157, v174, v175
	v_lshl_add_u64 v[160:161], v[158:159], 0, v[136:137]
	global_store_dwordx4 v[160:161], v[154:157], off nt
	s_nop 1
	v_mul_f32_e32 v154, 0xbfb8aa3b, v20
	v_mul_f32_e32 v155, 0xbfb8aa3b, v21
	v_mul_f32_e32 v156, 0xbfb8aa3b, v22
	v_mul_f32_e32 v157, 0xbfb8aa3b, v23
	v_mul_f32_e32 v160, 0xbfb8aa3b, v16
	v_mul_f32_e32 v161, 0xbfb8aa3b, v17
	v_mul_f32_e32 v174, 0xbfb8aa3b, v18
	v_mul_f32_e32 v175, 0xbfb8aa3b, v19
	v_exp_f32_e32 v154, v154
	v_exp_f32_e32 v155, v155
	v_exp_f32_e32 v156, v156
	v_exp_f32_e32 v157, v157
	v_exp_f32_e32 v160, v160
	v_exp_f32_e32 v161, v161
	v_exp_f32_e32 v174, v174
	v_exp_f32_e32 v175, v175
	v_add_f32_e32 v154, 1.0, v154
	v_add_f32_e32 v155, 1.0, v155
	v_add_f32_e32 v156, 1.0, v156
	v_add_f32_e32 v157, 1.0, v157
	v_add_f32_e32 v160, 1.0, v160
	v_add_f32_e32 v161, 1.0, v161
	v_add_f32_e32 v174, 1.0, v174
	v_add_f32_e32 v175, 1.0, v175
	v_rcp_f32_e32 v154, v154
	v_rcp_f32_e32 v155, v155
	v_rcp_f32_e32 v156, v156
	v_rcp_f32_e32 v157, v157
	v_rcp_f32_e32 v160, v160
	v_rcp_f32_e32 v161, v161
	v_rcp_f32_e32 v174, v174
	v_rcp_f32_e32 v175, v175
	v_cvt_pk_bf16_f32 v154, v154, v155
	v_cvt_pk_bf16_f32 v155, v156, v157
	v_cvt_pk_bf16_f32 v156, v160, v161
	v_cvt_pk_bf16_f32 v157, v174, v175
	v_lshl_add_u64 v[158:159], v[158:159], 0, v[152:153]
	global_store_dwordx4 v[158:159], v[154:157], off nt
	s_nop 1
	v_mul_f32_e32 v156, 0xbfb8aa3b, v12
	v_mul_f32_e32 v157, 0xbfb8aa3b, v13
	v_exp_f32_e32 v156, v156
	v_exp_f32_e32 v157, v157
	v_add_u32_e32 v154, s8, v169
	v_ashrrev_i32_e32 v155, 31, v154
	v_lshlrev_b64 v[158:159], 14, v[154:155]
	v_add_f32_e32 v154, 1.0, v156
	v_add_f32_e32 v155, 1.0, v157
	v_mul_f32_e32 v156, 0xbfb8aa3b, v14
	v_mul_f32_e32 v157, 0xbfb8aa3b, v15
	v_mul_f32_e32 v160, 0xbfb8aa3b, v8
	v_mul_f32_e32 v161, 0xbfb8aa3b, v9
	v_mul_f32_e32 v174, 0xbfb8aa3b, v10
	v_mul_f32_e32 v175, 0xbfb8aa3b, v11
	v_exp_f32_e32 v156, v156
	v_exp_f32_e32 v157, v157
	v_exp_f32_e32 v160, v160
	v_exp_f32_e32 v161, v161
	v_exp_f32_e32 v174, v174
	v_exp_f32_e32 v175, v175
	v_add_f32_e32 v156, 1.0, v156
	v_add_f32_e32 v157, 1.0, v157
	v_add_f32_e32 v160, 1.0, v160
	v_add_f32_e32 v161, 1.0, v161
	v_add_f32_e32 v174, 1.0, v174
	v_add_f32_e32 v175, 1.0, v175
	v_rcp_f32_e32 v154, v154
	v_rcp_f32_e32 v155, v155
	v_rcp_f32_e32 v156, v156
	v_rcp_f32_e32 v157, v157
	v_rcp_f32_e32 v160, v160
	v_rcp_f32_e32 v161, v161
	v_rcp_f32_e32 v174, v174
	v_rcp_f32_e32 v175, v175
	v_lshl_add_u64 v[158:159], s[18:19], 0, v[158:159]
	v_lshl_add_u64 v[158:159], v[158:159], 0, s[12:13]
	v_lshl_add_u64 v[158:159], v[158:159], 0, s[34:35]
	v_cvt_pk_bf16_f32 v154, v154, v155
	v_cvt_pk_bf16_f32 v155, v156, v157
	v_cvt_pk_bf16_f32 v156, v160, v161
	v_cvt_pk_bf16_f32 v157, v174, v175
	v_lshl_add_u64 v[160:161], v[158:159], 0, v[136:137]
	global_store_dwordx4 v[160:161], v[154:157], off nt
	v_mul_f32_e32 v136, 0xbfb8aa3b, v4
	s_nop 0
	v_mul_f32_e32 v154, 0xbfb8aa3b, v5
	v_mul_f32_e32 v155, 0xbfb8aa3b, v6
	v_mul_f32_e32 v156, 0xbfb8aa3b, v7
	v_mul_f32_e32 v157, 0xbfb8aa3b, v0
	v_mul_f32_e32 v160, 0xbfb8aa3b, v1
	v_mul_f32_e32 v161, 0xbfb8aa3b, v2
	v_mul_f32_e32 v174, 0xbfb8aa3b, v3
	v_exp_f32_e32 v136, v136
	v_exp_f32_e32 v154, v154
	v_exp_f32_e32 v155, v155
	v_exp_f32_e32 v156, v156
	v_exp_f32_e32 v157, v157
	v_exp_f32_e32 v160, v160
	v_exp_f32_e32 v161, v161
	v_exp_f32_e32 v174, v174
	v_add_f32_e32 v136, 1.0, v136
	v_add_f32_e32 v154, 1.0, v154
	v_add_f32_e32 v155, 1.0, v155
	v_add_f32_e32 v156, 1.0, v156
	v_add_f32_e32 v157, 1.0, v157
	v_add_f32_e32 v160, 1.0, v160
	v_add_f32_e32 v161, 1.0, v161
	v_add_f32_e32 v174, 1.0, v174
	v_rcp_f32_e32 v136, v136
	v_rcp_f32_e32 v154, v154
	v_rcp_f32_e32 v155, v155
	v_rcp_f32_e32 v156, v156
	v_rcp_f32_e32 v157, v157
	v_rcp_f32_e32 v160, v160
	v_rcp_f32_e32 v161, v161
	v_rcp_f32_e32 v174, v174
	v_cvt_pk_bf16_f32 v154, v136, v154
	v_cvt_pk_bf16_f32 v155, v155, v156
	v_cvt_pk_bf16_f32 v156, v157, v160
	v_cvt_pk_bf16_f32 v157, v161, v174
	v_lshl_add_u64 v[152:153], v[158:159], 0, v[152:153]
	global_store_dwordx4 v[152:153], v[154:157], off nt

.LBB0_256:
	s_andn2_b64 vcc, exec, s[8:9]
	s_cbranch_vccnz .LBB0_289
	s_sub_i32 s8, s46, 38
	s_cmp_lt_u32 s8, 4
	s_cselect_b64 s[50:51], -1, 0
	s_lshl_b32 s48, s46, 8
	s_ashr_i32 s49, s48, 31
	s_cmp_gt_u32 s46, 39
	s_cselect_b32 s9, 8, 0
	s_lshl_b32 s12, s46, 2
	s_and_b32 s12, s12, 4
	s_lshl_b32 s39, s44, 8
	s_or_b32 s12, s9, s12
	v_add_u32_e32 v152, s39, v139
	v_mov_b64_e32 v[158:159], s[16:17]
	s_cmp_gt_u32 s8, 3
	v_mad_i64_i32 v[158:159], s[8:9], v152, s66, v[158:159]
	v_lshl_add_u64 v[158:159], s[48:49], 1, v[158:159]
	v_lshlrev_b32_e32 v136, 1, v138
	v_cvt_pk_bf16_f32 v154, v124, v125
	v_cvt_pk_bf16_f32 v155, v126, v127
	v_cvt_pk_bf16_f32 v156, v120, v121
	v_cvt_pk_bf16_f32 v157, v122, v123
	v_lshl_add_u64 v[158:159], v[158:159], 0, v[136:137]
	global_store_dwordx4 v[158:159], v[154:157], off nt
	s_nop 1
	v_cvt_pk_bf16_f32 v154, v116, v117
	v_cvt_pk_bf16_f32 v155, v118, v119
	v_cvt_pk_bf16_f32 v156, v112, v113
	v_cvt_pk_bf16_f32 v157, v114, v115
	global_store_dwordx4 v[158:159], v[154:157], off offset:256 nt
	s_cbranch_scc1 .LBB0_261
	v_mul_f32_e32 v117, v117, v117
	v_fmac_f32_e32 v117, v116, v116
	v_mul_f32_e32 v125, v125, v125
	v_fmac_f32_e32 v117, v118, v118
	v_fmac_f32_e32 v125, v124, v124
	v_fmac_f32_e32 v117, v119, v119
	v_fmac_f32_e32 v125, v126, v126
	v_fmac_f32_e32 v117, v112, v112
	v_fmac_f32_e32 v125, v127, v127
	v_fmac_f32_e32 v117, v113, v113
	v_fmac_f32_e32 v125, v120, v120
	v_fmac_f32_e32 v117, v114, v114
	v_and_b32_e32 v114, 64, v173
	v_fmac_f32_e32 v125, v121, v121
	v_xor_b32_e32 v113, 16, v173
	v_add_u32_e32 v114, 64, v114
	v_fmac_f32_e32 v125, v122, v122
	v_cmp_lt_i32_e32 vcc, v113, v114
	v_fmac_f32_e32 v125, v123, v123
	v_fmac_f32_e32 v117, v115, v115
	v_cndmask_b32_e32 v113, v173, v113, vcc
	v_add_f32_e32 v112, v125, v117
	v_lshlrev_b32_e32 v113, 2, v113
	ds_bpermute_b32 v113, v113, v112
	s_waitcnt lgkmcnt(0)
	v_add_f32_e32 v112, v112, v113
	v_xor_b32_e32 v113, 32, v173
	v_cmp_lt_i32_e32 vcc, v113, v114
	s_nop 1
	v_cndmask_b32_e32 v113, v173, v113, vcc
	v_lshlrev_b32_e32 v113, 2, v113
	ds_bpermute_b32 v113, v113, v112
	s_and_saveexec_b64 s[8:9], s[4:5]
	s_cbranch_execz .LBB0_260
	v_lshl_or_b32 v114, v152, 4, s12
	v_or_b32_e32 v114, s58, v114
	v_ashrrev_i32_e32 v115, 31, v114
	v_lshl_add_u64 v[114:115], v[114:115], 2, s[20:21]
	s_waitcnt lgkmcnt(0)
	v_add_f32_e32 v112, v112, v113
	global_store_dword v[114:115], v112, off

.LBB0_261:
	v_add_u32_e32 v112, s39, v163
	v_mov_b64_e32 v[118:119], s[16:17]
	v_mad_i64_i32 v[118:119], s[8:9], v112, s66, v[118:119]
	v_lshl_add_u64 v[118:119], s[48:49], 1, v[118:119]
	v_cvt_pk_bf16_f32 v114, v108, v109
	v_cvt_pk_bf16_f32 v115, v110, v111
	v_cvt_pk_bf16_f32 v116, v104, v105
	v_cvt_pk_bf16_f32 v117, v106, v107
	v_lshl_add_u64 v[118:119], v[118:119], 0, v[136:137]
	global_store_dwordx4 v[118:119], v[114:117], off nt
	s_nop 1
	v_cvt_pk_bf16_f32 v114, v100, v101
	v_cvt_pk_bf16_f32 v115, v102, v103
	v_cvt_pk_bf16_f32 v116, v96, v97
	v_cvt_pk_bf16_f32 v117, v98, v99
	global_store_dwordx4 v[118:119], v[114:117], off offset:256 nt
	s_waitcnt lgkmcnt(0)
	v_cndmask_b32_e64 v113, 0, 1, s[50:51]
	v_cmp_ne_u32_e64 s[8:9], 1, v113
	s_andn2_b64 vcc, exec, s[50:51]
	s_cbranch_vccnz .LBB0_265
	v_mul_f32_e32 v101, v101, v101
	v_fmac_f32_e32 v101, v100, v100
	v_mul_f32_e32 v109, v109, v109
	v_fmac_f32_e32 v101, v102, v102
	v_fmac_f32_e32 v109, v108, v108
	v_fmac_f32_e32 v101, v103, v103
	v_fmac_f32_e32 v109, v110, v110
	v_fmac_f32_e32 v101, v96, v96
	v_fmac_f32_e32 v109, v111, v111
	v_fmac_f32_e32 v101, v97, v97
	v_fmac_f32_e32 v109, v104, v104
	v_fmac_f32_e32 v101, v98, v98
	v_and_b32_e32 v98, 64, v173
	v_fmac_f32_e32 v109, v105, v105
	v_xor_b32_e32 v97, 16, v173
	v_add_u32_e32 v98, 64, v98
	v_fmac_f32_e32 v109, v106, v106
	v_cmp_lt_i32_e32 vcc, v97, v98
	v_fmac_f32_e32 v109, v107, v107
	v_fmac_f32_e32 v101, v99, v99
	v_cndmask_b32_e32 v97, v173, v97, vcc
	v_add_f32_e32 v96, v109, v101
	v_lshlrev_b32_e32 v97, 2, v97
	ds_bpermute_b32 v97, v97, v96
	s_waitcnt lgkmcnt(0)
	v_add_f32_e32 v96, v96, v97
	v_xor_b32_e32 v97, 32, v173
	v_cmp_lt_i32_e32 vcc, v97, v98
	s_nop 1
	v_cndmask_b32_e32 v97, v173, v97, vcc
	v_lshlrev_b32_e32 v97, 2, v97
	ds_bpermute_b32 v97, v97, v96
	s_and_saveexec_b64 s[44:45], s[4:5]
	s_cbranch_execz .LBB0_264
	v_lshl_or_b32 v98, v112, 4, s12
	v_or_b32_e32 v98, s58, v98
	v_ashrrev_i32_e32 v99, 31, v98
	v_lshl_add_u64 v[98:99], v[98:99], 2, s[20:21]
	s_waitcnt lgkmcnt(0)
	v_add_f32_e32 v96, v96, v97
	global_store_dword v[98:99], v96, off

.LBB0_265:
	v_add_u32_e32 v96, s39, v164
	v_mov_b64_e32 v[102:103], s[16:17]
	v_mad_i64_i32 v[102:103], s[44:45], v96, s66, v[102:103]
	v_lshl_add_u64 v[102:103], s[48:49], 1, v[102:103]
	v_cvt_pk_bf16_f32 v98, v92, v93
	v_cvt_pk_bf16_f32 v99, v94, v95
	v_cvt_pk_bf16_f32 v100, v88, v89
	v_cvt_pk_bf16_f32 v101, v90, v91
	v_lshl_add_u64 v[102:103], v[102:103], 0, v[136:137]
	global_store_dwordx4 v[102:103], v[98:101], off nt
	s_nop 1
	v_cvt_pk_bf16_f32 v98, v84, v85
	v_cvt_pk_bf16_f32 v99, v86, v87
	v_cvt_pk_bf16_f32 v100, v80, v81
	v_cvt_pk_bf16_f32 v101, v82, v83
	global_store_dwordx4 v[102:103], v[98:101], off offset:256 nt
	s_and_b64 vcc, exec, s[8:9]
	s_cbranch_vccnz .LBB0_269
	v_mul_f32_e32 v85, v85, v85
	v_fmac_f32_e32 v85, v84, v84
	v_mul_f32_e32 v93, v93, v93
	v_fmac_f32_e32 v85, v86, v86
	v_fmac_f32_e32 v93, v92, v92
	v_fmac_f32_e32 v85, v87, v87
	v_fmac_f32_e32 v93, v94, v94
	v_fmac_f32_e32 v85, v80, v80
	v_fmac_f32_e32 v93, v95, v95
	v_fmac_f32_e32 v85, v81, v81
	v_fmac_f32_e32 v93, v88, v88
	v_fmac_f32_e32 v85, v82, v82
	v_and_b32_e32 v82, 64, v173
	v_fmac_f32_e32 v93, v89, v89
	v_xor_b32_e32 v81, 16, v173
	v_add_u32_e32 v82, 64, v82
	v_fmac_f32_e32 v93, v90, v90
	v_cmp_lt_i32_e32 vcc, v81, v82
	v_fmac_f32_e32 v93, v91, v91
	v_fmac_f32_e32 v85, v83, v83
	v_cndmask_b32_e32 v81, v173, v81, vcc
	v_add_f32_e32 v80, v93, v85
	v_lshlrev_b32_e32 v81, 2, v81
	ds_bpermute_b32 v81, v81, v80
	s_waitcnt lgkmcnt(0)
	v_add_f32_e32 v80, v80, v81
	v_xor_b32_e32 v81, 32, v173
	v_cmp_lt_i32_e32 vcc, v81, v82
	s_nop 1
	v_cndmask_b32_e32 v81, v173, v81, vcc
	v_lshlrev_b32_e32 v81, 2, v81
	ds_bpermute_b32 v81, v81, v80
	s_and_saveexec_b64 s[44:45], s[4:5]
	s_cbranch_execz .LBB0_268
	v_lshl_or_b32 v82, v96, 4, s12
	v_or_b32_e32 v82, s58, v82
	v_ashrrev_i32_e32 v83, 31, v82
	v_lshl_add_u64 v[82:83], v[82:83], 2, s[20:21]
	s_waitcnt lgkmcnt(0)
	v_add_f32_e32 v80, v80, v81
	global_store_dword v[82:83], v80, off

.LBB0_269:
	v_add_u32_e32 v80, s39, v165
	v_mov_b64_e32 v[86:87], s[16:17]
	v_mad_i64_i32 v[86:87], s[44:45], v80, s66, v[86:87]
	v_lshl_add_u64 v[86:87], s[48:49], 1, v[86:87]
	v_cvt_pk_bf16_f32 v82, v76, v77
	v_cvt_pk_bf16_f32 v83, v78, v79
	v_cvt_pk_bf16_f32 v84, v72, v73
	v_cvt_pk_bf16_f32 v85, v74, v75
	v_lshl_add_u64 v[86:87], v[86:87], 0, v[136:137]
	global_store_dwordx4 v[86:87], v[82:85], off nt
	s_nop 1
	v_cvt_pk_bf16_f32 v82, v68, v69
	v_cvt_pk_bf16_f32 v83, v70, v71
	v_cvt_pk_bf16_f32 v84, v64, v65
	v_cvt_pk_bf16_f32 v85, v66, v67
	global_store_dwordx4 v[86:87], v[82:85], off offset:256 nt
	s_and_b64 vcc, exec, s[8:9]
	s_cbranch_vccnz .LBB0_273
	v_mul_f32_e32 v69, v69, v69
	v_fmac_f32_e32 v69, v68, v68
	v_mul_f32_e32 v77, v77, v77
	v_fmac_f32_e32 v69, v70, v70
	v_fmac_f32_e32 v77, v76, v76
	v_fmac_f32_e32 v69, v71, v71
	v_fmac_f32_e32 v77, v78, v78
	v_fmac_f32_e32 v69, v64, v64
	v_fmac_f32_e32 v77, v79, v79
	v_fmac_f32_e32 v69, v65, v65
	v_fmac_f32_e32 v77, v72, v72
	v_fmac_f32_e32 v69, v66, v66
	v_and_b32_e32 v66, 64, v173
	v_fmac_f32_e32 v77, v73, v73
	v_xor_b32_e32 v65, 16, v173
	v_add_u32_e32 v66, 64, v66
	v_fmac_f32_e32 v77, v74, v74
	v_cmp_lt_i32_e32 vcc, v65, v66
	v_fmac_f32_e32 v77, v75, v75
	v_fmac_f32_e32 v69, v67, v67
	v_cndmask_b32_e32 v65, v173, v65, vcc
	v_add_f32_e32 v64, v77, v69
	v_lshlrev_b32_e32 v65, 2, v65
	ds_bpermute_b32 v65, v65, v64
	s_waitcnt lgkmcnt(0)
	v_add_f32_e32 v64, v64, v65
	v_xor_b32_e32 v65, 32, v173
	v_cmp_lt_i32_e32 vcc, v65, v66
	s_nop 1
	v_cndmask_b32_e32 v65, v173, v65, vcc
	v_lshlrev_b32_e32 v65, 2, v65
	ds_bpermute_b32 v65, v65, v64
	s_and_saveexec_b64 s[44:45], s[4:5]
	s_cbranch_execz .LBB0_272
	v_lshl_or_b32 v66, v80, 4, s12
	v_or_b32_e32 v66, s58, v66
	v_ashrrev_i32_e32 v67, 31, v66
	v_lshl_add_u64 v[66:67], v[66:67], 2, s[20:21]
	s_waitcnt lgkmcnt(0)
	v_add_f32_e32 v64, v64, v65
	global_store_dword v[66:67], v64, off

.LBB0_273:
	v_add_u32_e32 v64, s39, v166
	v_mov_b64_e32 v[70:71], s[16:17]
	v_mad_i64_i32 v[70:71], s[44:45], v64, s66, v[70:71]
	v_lshl_add_u64 v[70:71], s[48:49], 1, v[70:71]
	v_cvt_pk_bf16_f32 v66, v60, v61
	v_cvt_pk_bf16_f32 v67, v62, v63
	v_cvt_pk_bf16_f32 v68, v56, v57
	v_cvt_pk_bf16_f32 v69, v58, v59
	v_lshl_add_u64 v[70:71], v[70:71], 0, v[136:137]
	global_store_dwordx4 v[70:71], v[66:69], off nt
	s_nop 1
	v_cvt_pk_bf16_f32 v66, v52, v53
	v_cvt_pk_bf16_f32 v67, v54, v55
	v_cvt_pk_bf16_f32 v68, v48, v49
	v_cvt_pk_bf16_f32 v69, v50, v51
	global_store_dwordx4 v[70:71], v[66:69], off offset:256 nt
	s_and_b64 vcc, exec, s[8:9]
	s_cbranch_vccnz .LBB0_277
	v_mul_f32_e32 v53, v53, v53
	v_fmac_f32_e32 v53, v52, v52
	v_mul_f32_e32 v61, v61, v61
	v_fmac_f32_e32 v53, v54, v54
	v_fmac_f32_e32 v61, v60, v60
	v_fmac_f32_e32 v53, v55, v55
	v_fmac_f32_e32 v61, v62, v62
	v_fmac_f32_e32 v53, v48, v48
	v_fmac_f32_e32 v61, v63, v63
	v_fmac_f32_e32 v53, v49, v49
	v_fmac_f32_e32 v61, v56, v56
	v_fmac_f32_e32 v53, v50, v50
	v_and_b32_e32 v50, 64, v173
	v_fmac_f32_e32 v61, v57, v57
	v_xor_b32_e32 v49, 16, v173
	v_add_u32_e32 v50, 64, v50
	v_fmac_f32_e32 v61, v58, v58
	v_cmp_lt_i32_e32 vcc, v49, v50
	v_fmac_f32_e32 v61, v59, v59
	v_fmac_f32_e32 v53, v51, v51
	v_cndmask_b32_e32 v49, v173, v49, vcc
	v_add_f32_e32 v48, v61, v53
	v_lshlrev_b32_e32 v49, 2, v49
	ds_bpermute_b32 v49, v49, v48
	s_waitcnt lgkmcnt(0)
	v_add_f32_e32 v48, v48, v49
	v_xor_b32_e32 v49, 32, v173
	v_cmp_lt_i32_e32 vcc, v49, v50
	s_nop 1
	v_cndmask_b32_e32 v49, v173, v49, vcc
	v_lshlrev_b32_e32 v49, 2, v49
	ds_bpermute_b32 v49, v49, v48
	s_and_saveexec_b64 s[44:45], s[4:5]
	s_cbranch_execz .LBB0_276
	v_lshl_or_b32 v50, v64, 4, s12
	v_or_b32_e32 v50, s58, v50
	v_ashrrev_i32_e32 v51, 31, v50
	v_lshl_add_u64 v[50:51], v[50:51], 2, s[20:21]
	s_waitcnt lgkmcnt(0)
	v_add_f32_e32 v48, v48, v49
	global_store_dword v[50:51], v48, off

.LBB0_277:
	v_add_u32_e32 v48, s39, v167
	v_mov_b64_e32 v[54:55], s[16:17]
	v_mad_i64_i32 v[54:55], s[44:45], v48, s66, v[54:55]
	v_lshl_add_u64 v[54:55], s[48:49], 1, v[54:55]
	v_cvt_pk_bf16_f32 v50, v44, v45
	v_cvt_pk_bf16_f32 v51, v46, v47
	v_cvt_pk_bf16_f32 v52, v40, v41
	v_cvt_pk_bf16_f32 v53, v42, v43
	v_lshl_add_u64 v[54:55], v[54:55], 0, v[136:137]
	global_store_dwordx4 v[54:55], v[50:53], off nt
	s_nop 1
	v_cvt_pk_bf16_f32 v50, v36, v37
	v_cvt_pk_bf16_f32 v51, v38, v39
	v_cvt_pk_bf16_f32 v52, v32, v33
	v_cvt_pk_bf16_f32 v53, v34, v35
	global_store_dwordx4 v[54:55], v[50:53], off offset:256 nt
	s_and_b64 vcc, exec, s[8:9]
	s_cbranch_vccnz .LBB0_281
	v_mul_f32_e32 v37, v37, v37
	v_fmac_f32_e32 v37, v36, v36
	v_mul_f32_e32 v45, v45, v45
	v_fmac_f32_e32 v37, v38, v38
	v_fmac_f32_e32 v45, v44, v44
	v_fmac_f32_e32 v37, v39, v39
	v_fmac_f32_e32 v45, v46, v46
	v_fmac_f32_e32 v37, v32, v32
	v_fmac_f32_e32 v45, v47, v47
	v_fmac_f32_e32 v37, v33, v33
	v_fmac_f32_e32 v45, v40, v40
	v_fmac_f32_e32 v37, v34, v34
	v_and_b32_e32 v34, 64, v173
	v_fmac_f32_e32 v45, v41, v41
	v_xor_b32_e32 v33, 16, v173
	v_add_u32_e32 v34, 64, v34
	v_fmac_f32_e32 v45, v42, v42
	v_cmp_lt_i32_e32 vcc, v33, v34
	v_fmac_f32_e32 v45, v43, v43
	v_fmac_f32_e32 v37, v35, v35
	v_cndmask_b32_e32 v33, v173, v33, vcc
	v_add_f32_e32 v32, v45, v37
	v_lshlrev_b32_e32 v33, 2, v33
	ds_bpermute_b32 v33, v33, v32
	s_waitcnt lgkmcnt(0)
	v_add_f32_e32 v32, v32, v33
	v_xor_b32_e32 v33, 32, v173
	v_cmp_lt_i32_e32 vcc, v33, v34
	s_nop 1
	v_cndmask_b32_e32 v33, v173, v33, vcc
	v_lshlrev_b32_e32 v33, 2, v33
	ds_bpermute_b32 v33, v33, v32
	s_and_saveexec_b64 s[44:45], s[4:5]
	s_cbranch_execz .LBB0_280
	v_lshl_or_b32 v34, v48, 4, s12
	v_or_b32_e32 v34, s58, v34
	v_ashrrev_i32_e32 v35, 31, v34
	v_lshl_add_u64 v[34:35], v[34:35], 2, s[20:21]
	s_waitcnt lgkmcnt(0)
	v_add_f32_e32 v32, v32, v33
	global_store_dword v[34:35], v32, off

.LBB0_281:
	v_add_u32_e32 v32, s39, v168
	v_mov_b64_e32 v[38:39], s[16:17]
	v_mad_i64_i32 v[38:39], s[44:45], v32, s66, v[38:39]
	v_lshl_add_u64 v[38:39], s[48:49], 1, v[38:39]
	v_cvt_pk_bf16_f32 v34, v28, v29
	v_cvt_pk_bf16_f32 v35, v30, v31
	v_cvt_pk_bf16_f32 v36, v24, v25
	v_cvt_pk_bf16_f32 v37, v26, v27
	v_lshl_add_u64 v[38:39], v[38:39], 0, v[136:137]
	global_store_dwordx4 v[38:39], v[34:37], off nt
	s_nop 1
	v_cvt_pk_bf16_f32 v34, v20, v21
	v_cvt_pk_bf16_f32 v35, v22, v23
	v_cvt_pk_bf16_f32 v36, v16, v17
	v_cvt_pk_bf16_f32 v37, v18, v19
	global_store_dwordx4 v[38:39], v[34:37], off offset:256 nt
	s_and_b64 vcc, exec, s[8:9]
	s_cbranch_vccnz .LBB0_285
	v_mul_f32_e32 v21, v21, v21
	v_fmac_f32_e32 v21, v20, v20
	v_mul_f32_e32 v29, v29, v29
	v_fmac_f32_e32 v21, v22, v22
	v_fmac_f32_e32 v29, v28, v28
	v_fmac_f32_e32 v21, v23, v23
	v_fmac_f32_e32 v29, v30, v30
	v_fmac_f32_e32 v21, v16, v16
	v_fmac_f32_e32 v29, v31, v31
	v_fmac_f32_e32 v21, v17, v17
	v_fmac_f32_e32 v29, v24, v24
	v_fmac_f32_e32 v21, v18, v18
	v_and_b32_e32 v18, 64, v173
	v_fmac_f32_e32 v29, v25, v25
	v_xor_b32_e32 v17, 16, v173
	v_add_u32_e32 v18, 64, v18
	v_fmac_f32_e32 v29, v26, v26
	v_cmp_lt_i32_e32 vcc, v17, v18
	v_fmac_f32_e32 v29, v27, v27
	v_fmac_f32_e32 v21, v19, v19
	v_cndmask_b32_e32 v17, v173, v17, vcc
	v_add_f32_e32 v16, v29, v21
	v_lshlrev_b32_e32 v17, 2, v17
	ds_bpermute_b32 v17, v17, v16
	s_waitcnt lgkmcnt(0)
	v_add_f32_e32 v16, v16, v17
	v_xor_b32_e32 v17, 32, v173
	v_cmp_lt_i32_e32 vcc, v17, v18
	s_nop 1
	v_cndmask_b32_e32 v17, v173, v17, vcc
	v_lshlrev_b32_e32 v17, 2, v17
	ds_bpermute_b32 v17, v17, v16
	s_and_saveexec_b64 s[44:45], s[4:5]
	s_cbranch_execz .LBB0_284
	v_lshl_or_b32 v18, v32, 4, s12
	v_or_b32_e32 v18, s58, v18
	v_ashrrev_i32_e32 v19, 31, v18
	v_lshl_add_u64 v[18:19], v[18:19], 2, s[20:21]
	s_waitcnt lgkmcnt(0)
	v_add_f32_e32 v16, v16, v17
	global_store_dword v[18:19], v16, off

.LBB0_285:
	v_add_u32_e32 v16, s39, v169
	v_mov_b64_e32 v[22:23], s[16:17]
	v_mad_i64_i32 v[22:23], s[44:45], v16, s66, v[22:23]
	v_lshl_add_u64 v[22:23], s[48:49], 1, v[22:23]
	v_cvt_pk_bf16_f32 v18, v12, v13
	v_cvt_pk_bf16_f32 v19, v14, v15
	v_cvt_pk_bf16_f32 v20, v8, v9
	v_cvt_pk_bf16_f32 v21, v10, v11
	v_lshl_add_u64 v[22:23], v[22:23], 0, v[136:137]
	global_store_dwordx4 v[22:23], v[18:21], off nt
	s_nop 1
	v_cvt_pk_bf16_f32 v18, v4, v5
	v_cvt_pk_bf16_f32 v19, v6, v7
	v_cvt_pk_bf16_f32 v20, v0, v1
	v_cvt_pk_bf16_f32 v21, v2, v3
	global_store_dwordx4 v[22:23], v[18:21], off offset:256 nt
	s_and_b64 vcc, exec, s[8:9]
	s_cbranch_vccnz .LBB0_289
	v_mul_f32_e32 v5, v5, v5
	v_fmac_f32_e32 v5, v4, v4
	v_mul_f32_e32 v13, v13, v13
	v_fmac_f32_e32 v5, v6, v6
	v_fmac_f32_e32 v13, v12, v12
	v_fmac_f32_e32 v5, v7, v7
	v_fmac_f32_e32 v13, v14, v14
	v_fmac_f32_e32 v5, v0, v0
	v_fmac_f32_e32 v13, v15, v15
	v_fmac_f32_e32 v5, v1, v1
	v_fmac_f32_e32 v13, v8, v8
	v_fmac_f32_e32 v5, v2, v2
	v_and_b32_e32 v2, 64, v173
	v_fmac_f32_e32 v13, v9, v9
	v_xor_b32_e32 v1, 16, v173
	v_add_u32_e32 v2, 64, v2
	v_fmac_f32_e32 v13, v10, v10
	v_cmp_lt_i32_e32 vcc, v1, v2
	v_fmac_f32_e32 v13, v11, v11
	v_fmac_f32_e32 v5, v3, v3
	v_cndmask_b32_e32 v1, v173, v1, vcc
	v_add_f32_e32 v0, v13, v5
	v_lshlrev_b32_e32 v1, 2, v1
	ds_bpermute_b32 v1, v1, v0
	s_waitcnt lgkmcnt(0)
	v_add_f32_e32 v0, v0, v1
	v_xor_b32_e32 v1, 32, v173
	v_cmp_lt_i32_e32 vcc, v1, v2
	s_nop 1
	v_cndmask_b32_e32 v1, v173, v1, vcc
	v_lshlrev_b32_e32 v1, 2, v1
	ds_bpermute_b32 v1, v1, v0
	s_and_saveexec_b64 s[8:9], s[4:5]
	s_cbranch_execz .LBB0_288
	v_lshl_or_b32 v2, v16, 4, s12
	v_or_b32_e32 v2, s58, v2
	v_ashrrev_i32_e32 v3, 31, v2
	v_lshl_add_u64 v[2:3], v[2:3], 2, s[20:21]
	s_waitcnt lgkmcnt(0)
	v_add_f32_e32 v0, v0, v1
	global_store_dword v[2:3], v0, off
